# v72 + pmat loop's last MFMA chain: eight serialized K-fragment LDS reads issued ahead with counted lgkmcnt
# baseline (speedup 1.0000x reference)
; #define GAS __attribute__((address_space(1)))
; #define LAS __attribute__((address_space(3)))
; __device__ __forceinline__ unsigned cvt_pk_bf16(float lo, float hi) { unsigned r; asm volatile("v_cvt_pk_bf16_f32 %0, %1, %2" : "=v"(r) : "v"(lo), "v"(hi)); return r; }
; __device__ __forceinline__ void pmat_phase(const Frame& F, const bf16_t* Q, const bf16_t* K, bf16_t* PB, int half) {
;     ...
;         bf16x8 Qf[8];
; #pragma unroll
;         for (int ks = 0; ks < 8; ++ks) Qf[ks] = *(const LAS bf16x8*)(bQown + 64 * ks);
;         bf16_t* pout = PB + (size_t)u * 16384; const unsigned lpo = (unsigned)((16 * wv + l15) * 128 + 4 * quad); const int i_abs = 16 * wv + l15;
; #pragma unroll
;         for (int jt = 0; jt < 8; ++jt) { f32x4 st = {0.f, 0.f, 0.f, 0.f};
; #pragma unroll
;             for (int ks = 0; ks < 8; ++ks) { const bf16x8 Kf = *(const LAS bf16x8*)(bK + 16 * jt * PS + 64 * ks); st = __builtin_amdgcn_mfma_f32_16x16x32_bf16(Kf, Qf[ks], st, 0, 0, 0); }
; #pragma unroll
;             for (int r = 0; r < 4; ++r) { const int jj = 16 * jt + 4 * quad + r;
;                 st[r] *= __builtin_amdgcn_exp2f(jj <= i_abs ? lgf * (float)(-jj - 1) : lgb * (float)(jj - 128)); }
;             *(GAS u32x2*)(pout + 16 * jt + lpo) = (u32x2){cvt_pk_bf16(st[0], st[1]), cvt_pk_bf16(st[2], st[3])}; }
.Lpmat_nopf:
	ds_read_b128 v[28:31], v106
	ds_read_b128 v[24:27], v106 offset:64
	ds_read_b128 v[20:23], v106 offset:128
	ds_read_b128 v[16:19], v106 offset:192
	ds_read_b128 v[12:15], v106 offset:256
	ds_read_b128 v[8:11], v106 offset:320
	ds_read_b128 v[4:7], v106 offset:384
	ds_read_b128 v[0:3], v106 offset:448
	ds_read_b128 v[108:111], v38
	ds_read_b128 v[112:115], v38 offset:64
	ds_read_b128 v[116:119], v38 offset:128
	ds_read_b128 v[120:123], v38 offset:192
	ds_read_b128 v[124:127], v38 offset:256
	s_waitcnt lgkmcnt(4)
	v_mfma_f32_16x16x32_bf16 v[108:111], v[108:111], v[28:31], 0
	s_waitcnt lgkmcnt(3)
	v_mfma_f32_16x16x32_bf16 v[108:111], v[112:115], v[24:27], v[108:111]
	ds_read_b128 v[112:115], v38 offset:320
	s_waitcnt lgkmcnt(3)
	v_mfma_f32_16x16x32_bf16 v[108:111], v[116:119], v[20:23], v[108:111]
	ds_read_b128 v[116:119], v38 offset:384
	s_waitcnt lgkmcnt(3)
	v_mfma_f32_16x16x32_bf16 v[108:111], v[120:123], v[16:19], v[108:111]
	ds_read_b128 v[120:123], v38 offset:448
	s_waitcnt lgkmcnt(3)
	v_mfma_f32_16x16x32_bf16 v[108:111], v[124:127], v[12:15], v[108:111]
	s_waitcnt lgkmcnt(2)
	v_mfma_f32_16x16x32_bf16 v[108:111], v[112:115], v[8:11], v[108:111]
	s_waitcnt lgkmcnt(1)
	v_mfma_f32_16x16x32_bf16 v[108:111], v[116:119], v[4:7], v[108:111]
	s_waitcnt lgkmcnt(0)
	v_mfma_f32_16x16x32_bf16 v[108:111], v[120:123], v[0:3], v[108:111]
	v_mul_f32_e32 v112, s12, v40
	v_cndmask_b32_e64 v107, v107, v112, s[0:1]
	v_exp_f32_e32 v107, v107
	v_mul_f32_e32 v112, s12, v41
	s_nop 3
	v_mul_f32_e32 v107, v107, v108
	v_mul_f32_e32 v108, s23, v42
	v_cndmask_b32_e64 v108, v112, v108, s[34:35]
	v_exp_f32_e32 v108, v108
	v_mul_f32_e32 v112, s12, v44
	v_mul_f32_e32 v108, v108, v109
	v_mul_f32_e32 v109, s23, v43
	v_cndmask_b32_e64 v109, v109, v112, s[36:37]
	v_exp_f32_e32 v109, v109
	v_mul_f32_e32 v112, s12, v46
	v_cvt_pk_bf16_f32 v108, v107, v108
	v_mul_f32_e32 v107, s23, v47
	v_mul_f32_e32 v109, v109, v110
	v_mul_f32_e32 v110, s23, v45
	v_cndmask_b32_e64 v110, v110, v112, s[38:39]
	v_exp_f32_e32 v110, v110
	s_nop 0
	v_mul_f32_e32 v110, v110, v111
	v_cvt_pk_bf16_f32 v109, v109, v110
	global_store_dwordx2 v[36:37], v[108:109], off
	ds_read_b128 v[108:111], v38 offset:8448
	ds_read_b128 v[112:115], v38 offset:8512
	ds_read_b128 v[116:119], v38 offset:8576
	ds_read_b128 v[120:123], v38 offset:8640
	ds_read_b128 v[124:127], v38 offset:8704
	s_waitcnt lgkmcnt(4)
	v_mfma_f32_16x16x32_bf16 v[108:111], v[108:111], v[28:31], 0
	s_waitcnt lgkmcnt(3)
	v_mfma_f32_16x16x32_bf16 v[108:111], v[112:115], v[24:27], v[108:111]
	ds_read_b128 v[112:115], v38 offset:8768
	s_waitcnt lgkmcnt(3)
	v_mfma_f32_16x16x32_bf16 v[108:111], v[116:119], v[20:23], v[108:111]
	ds_read_b128 v[116:119], v38 offset:8832
	s_waitcnt lgkmcnt(3)
	v_mfma_f32_16x16x32_bf16 v[108:111], v[120:123], v[16:19], v[108:111]
	ds_read_b128 v[120:123], v38 offset:8896
	s_waitcnt lgkmcnt(3)
	v_mfma_f32_16x16x32_bf16 v[108:111], v[124:127], v[12:15], v[108:111]
	s_waitcnt lgkmcnt(2)
	v_mfma_f32_16x16x32_bf16 v[108:111], v[112:115], v[8:11], v[108:111]
	s_waitcnt lgkmcnt(1)
	v_mfma_f32_16x16x32_bf16 v[108:111], v[116:119], v[4:7], v[108:111]
	s_waitcnt lgkmcnt(0)
	v_mfma_f32_16x16x32_bf16 v[108:111], v[120:123], v[0:3], v[108:111]
	v_mul_f32_e32 v112, s12, v48
	v_cndmask_b32_e64 v107, v107, v112, s[40:41]
	v_exp_f32_e32 v107, v107
	v_mul_f32_e32 v112, s12, v50
	s_nop 3
	v_mul_f32_e32 v107, v107, v108
	v_mul_f32_e32 v108, s23, v49
	v_cndmask_b32_e64 v108, v108, v112, s[42:43]
	v_exp_f32_e32 v108, v108
	v_mul_f32_e32 v112, s12, v52
	v_mul_f32_e32 v108, v108, v109
	v_mul_f32_e32 v109, s23, v51
	v_cndmask_b32_e64 v109, v109, v112, s[44:45]
	v_exp_f32_e32 v109, v109
	v_mul_f32_e32 v112, s12, v54
	v_cvt_pk_bf16_f32 v108, v107, v108
	v_mul_f32_e32 v107, s23, v55
	v_mul_f32_e32 v109, v109, v110
	v_mul_f32_e32 v110, s23, v53
	v_cndmask_b32_e64 v110, v110, v112, s[46:47]
	v_exp_f32_e32 v110, v110
	s_nop 0
	v_mul_f32_e32 v110, v110, v111
	v_cvt_pk_bf16_f32 v109, v109, v110
	global_store_dwordx2 v[36:37], v[108:109], off offset:32
	ds_read_b128 v[108:111], v38 offset:16896
	ds_read_b128 v[112:115], v38 offset:16960
	ds_read_b128 v[116:119], v38 offset:17024
	ds_read_b128 v[120:123], v38 offset:17088
	ds_read_b128 v[124:127], v38 offset:17152
	s_waitcnt lgkmcnt(4)
	v_mfma_f32_16x16x32_bf16 v[108:111], v[108:111], v[28:31], 0
	s_waitcnt lgkmcnt(3)
	v_mfma_f32_16x16x32_bf16 v[108:111], v[112:115], v[24:27], v[108:111]
	ds_read_b128 v[112:115], v38 offset:17216
	s_waitcnt lgkmcnt(3)
	v_mfma_f32_16x16x32_bf16 v[108:111], v[116:119], v[20:23], v[108:111]
	ds_read_b128 v[116:119], v38 offset:17280
	s_waitcnt lgkmcnt(3)
	v_mfma_f32_16x16x32_bf16 v[108:111], v[120:123], v[16:19], v[108:111]
	ds_read_b128 v[120:123], v38 offset:17344
	s_waitcnt lgkmcnt(3)
	v_mfma_f32_16x16x32_bf16 v[108:111], v[124:127], v[12:15], v[108:111]
	s_waitcnt lgkmcnt(2)
	v_mfma_f32_16x16x32_bf16 v[108:111], v[112:115], v[8:11], v[108:111]
	s_waitcnt lgkmcnt(1)
	v_mfma_f32_16x16x32_bf16 v[108:111], v[116:119], v[4:7], v[108:111]
	s_waitcnt lgkmcnt(0)
	v_mfma_f32_16x16x32_bf16 v[108:111], v[120:123], v[0:3], v[108:111]
	v_mul_f32_e32 v112, s12, v56
	v_cndmask_b32_e64 v107, v107, v112, s[48:49]
	v_exp_f32_e32 v107, v107
	v_mul_f32_e32 v112, s12, v58
	s_nop 3
	v_mul_f32_e32 v107, v107, v108
	v_mul_f32_e32 v108, s23, v57
	v_cndmask_b32_e64 v108, v108, v112, s[50:51]
	v_exp_f32_e32 v108, v108
	v_mul_f32_e32 v112, s12, v60
	v_mul_f32_e32 v108, v108, v109
	v_mul_f32_e32 v109, s23, v59
	v_cndmask_b32_e64 v109, v109, v112, s[52:53]
	v_exp_f32_e32 v109, v109
	v_mul_f32_e32 v112, s12, v62
	v_cvt_pk_bf16_f32 v108, v107, v108
	v_mul_f32_e32 v107, s23, v63
	v_mul_f32_e32 v109, v109, v110
	v_mul_f32_e32 v110, s23, v61
	v_cndmask_b32_e64 v110, v110, v112, s[54:55]
	v_exp_f32_e32 v110, v110
	s_nop 0
	v_mul_f32_e32 v110, v110, v111
	v_cvt_pk_bf16_f32 v109, v109, v110
	global_store_dwordx2 v[36:37], v[108:109], off offset:64
	ds_read_b128 v[108:111], v38 offset:25344
	ds_read_b128 v[112:115], v38 offset:25408
	ds_read_b128 v[116:119], v38 offset:25472
	ds_read_b128 v[120:123], v38 offset:25536
	ds_read_b128 v[124:127], v38 offset:25600
	s_waitcnt lgkmcnt(4)
; #define GAS __attribute__((address_space(1)))
; #define LAS __attribute__((address_space(3)))
; __device__ __forceinline__ unsigned cvt_pk_bf16(float lo, float hi) { unsigned r; asm volatile("v_cvt_pk_bf16_f32 %0, %1, %2" : "=v"(r) : "v"(lo), "v"(hi)); return r; }
; __device__ __forceinline__ void pmat_phase(const Frame& F, const bf16_t* Q, const bf16_t* K, bf16_t* PB, int half) {
;     ...
;         for (int jt = 0; jt < 8; ++jt) { f32x4 st = {0.f, 0.f, 0.f, 0.f};
; #pragma unroll
;             for (int ks = 0; ks < 8; ++ks) { const bf16x8 Kf = *(const LAS bf16x8*)(bK + 16 * jt * PS + 64 * ks); st = __builtin_amdgcn_mfma_f32_16x16x32_bf16(Kf, Qf[ks], st, 0, 0, 0); }
; #pragma unroll
;             for (int r = 0; r < 4; ++r) { const int jj = 16 * jt + 4 * quad + r;
;                 st[r] *= __builtin_amdgcn_exp2f(jj <= i_abs ? lgf * (float)(-jj - 1) : lgb * (float)(jj - 128)); }
;             *(GAS u32x2*)(pout + 16 * jt + lpo) = (u32x2){cvt_pk_bf16(st[0], st[1]), cvt_pk_bf16(st[2], st[3])}; }
	v_mfma_f32_16x16x32_bf16 v[108:111], v[108:111], v[28:31], 0
	s_waitcnt lgkmcnt(3)
	v_mfma_f32_16x16x32_bf16 v[108:111], v[112:115], v[24:27], v[108:111]
	ds_read_b128 v[112:115], v38 offset:25664
	s_waitcnt lgkmcnt(3)
	v_mfma_f32_16x16x32_bf16 v[108:111], v[116:119], v[20:23], v[108:111]
	ds_read_b128 v[116:119], v38 offset:25728
	s_waitcnt lgkmcnt(3)
	v_mfma_f32_16x16x32_bf16 v[108:111], v[120:123], v[16:19], v[108:111]
	ds_read_b128 v[120:123], v38 offset:25792
	s_waitcnt lgkmcnt(3)
	v_mfma_f32_16x16x32_bf16 v[108:111], v[124:127], v[12:15], v[108:111]
	s_waitcnt lgkmcnt(2)
	v_mfma_f32_16x16x32_bf16 v[108:111], v[112:115], v[8:11], v[108:111]
	s_waitcnt lgkmcnt(1)
	v_mfma_f32_16x16x32_bf16 v[108:111], v[116:119], v[4:7], v[108:111]
	s_waitcnt lgkmcnt(0)
	v_mfma_f32_16x16x32_bf16 v[108:111], v[120:123], v[0:3], v[108:111]
	v_mul_f32_e32 v112, s12, v64
	v_cndmask_b32_e64 v107, v107, v112, s[56:57]
	v_exp_f32_e32 v107, v107
	v_mul_f32_e32 v112, s12, v66
	s_nop 3
	v_mul_f32_e32 v107, v107, v108
	v_mul_f32_e32 v108, s23, v65
	v_cndmask_b32_e64 v108, v108, v112, s[58:59]
	v_exp_f32_e32 v108, v108
	v_mul_f32_e32 v112, s12, v68
	v_mul_f32_e32 v108, v108, v109
	v_mul_f32_e32 v109, s23, v67
	v_cndmask_b32_e64 v109, v109, v112, s[60:61]
	v_exp_f32_e32 v109, v109
	v_mul_f32_e32 v112, s12, v70
	v_cvt_pk_bf16_f32 v108, v107, v108
	v_mul_f32_e32 v107, s23, v71
	v_mul_f32_e32 v109, v109, v110
	v_mul_f32_e32 v110, s23, v69
	v_cndmask_b32_e64 v110, v110, v112, s[62:63]
	v_exp_f32_e32 v110, v110
	s_nop 0
	v_mul_f32_e32 v110, v110, v111
	v_cvt_pk_bf16_f32 v109, v109, v110
	global_store_dwordx2 v[36:37], v[108:109], off offset:96
	ds_read_b128 v[108:111], v38 offset:33792
	ds_read_b128 v[112:115], v38 offset:33856
	ds_read_b128 v[116:119], v38 offset:33920
	ds_read_b128 v[120:123], v38 offset:33984
	ds_read_b128 v[124:127], v38 offset:34048
	s_waitcnt lgkmcnt(4)
	v_mfma_f32_16x16x32_bf16 v[108:111], v[108:111], v[28:31], 0
	s_waitcnt lgkmcnt(3)
	v_mfma_f32_16x16x32_bf16 v[108:111], v[112:115], v[24:27], v[108:111]
	ds_read_b128 v[112:115], v38 offset:34112
	s_waitcnt lgkmcnt(3)
	v_mfma_f32_16x16x32_bf16 v[108:111], v[116:119], v[20:23], v[108:111]
	ds_read_b128 v[116:119], v38 offset:34176
	s_waitcnt lgkmcnt(3)
	v_mfma_f32_16x16x32_bf16 v[108:111], v[120:123], v[16:19], v[108:111]
	ds_read_b128 v[120:123], v38 offset:34240
	s_waitcnt lgkmcnt(3)
	v_mfma_f32_16x16x32_bf16 v[108:111], v[124:127], v[12:15], v[108:111]
	s_waitcnt lgkmcnt(2)
	v_mfma_f32_16x16x32_bf16 v[108:111], v[112:115], v[8:11], v[108:111]
	s_waitcnt lgkmcnt(1)
	v_mfma_f32_16x16x32_bf16 v[108:111], v[116:119], v[4:7], v[108:111]
	s_waitcnt lgkmcnt(0)
	v_mfma_f32_16x16x32_bf16 v[108:111], v[120:123], v[0:3], v[108:111]
	v_mul_f32_e32 v112, s12, v72
	v_cndmask_b32_e64 v107, v107, v112, s[64:65]
	v_exp_f32_e32 v107, v107
	v_mul_f32_e32 v112, s12, v74
	s_nop 3
	v_mul_f32_e32 v107, v107, v108
	v_mul_f32_e32 v108, s23, v73
	v_cndmask_b32_e64 v108, v108, v112, s[66:67]
	v_exp_f32_e32 v108, v108
	v_mul_f32_e32 v112, s12, v76
	v_mul_f32_e32 v108, v108, v109
	v_mul_f32_e32 v109, s23, v75
	v_cndmask_b32_e64 v109, v109, v112, s[68:69]
	v_exp_f32_e32 v109, v109
	v_mul_f32_e32 v112, s12, v78
	v_cvt_pk_bf16_f32 v108, v107, v108
	v_mul_f32_e32 v107, s23, v79
	v_mul_f32_e32 v109, v109, v110
	v_mul_f32_e32 v110, s23, v77
	v_cndmask_b32_e64 v110, v110, v112, s[70:71]
	v_exp_f32_e32 v110, v110
	s_nop 0
	v_mul_f32_e32 v110, v110, v111
	v_cvt_pk_bf16_f32 v109, v109, v110
	global_store_dwordx2 v[36:37], v[108:109], off offset:128
	ds_read_b128 v[108:111], v38 offset:42240
	ds_read_b128 v[112:115], v38 offset:42304
	ds_read_b128 v[116:119], v38 offset:42368
	ds_read_b128 v[120:123], v38 offset:42432
	ds_read_b128 v[124:127], v38 offset:42496
	s_waitcnt lgkmcnt(4)
	v_mfma_f32_16x16x32_bf16 v[108:111], v[108:111], v[28:31], 0
	s_waitcnt lgkmcnt(3)
	v_mfma_f32_16x16x32_bf16 v[108:111], v[112:115], v[24:27], v[108:111]
	ds_read_b128 v[112:115], v38 offset:42560
	s_waitcnt lgkmcnt(3)
	v_mfma_f32_16x16x32_bf16 v[108:111], v[116:119], v[20:23], v[108:111]
	ds_read_b128 v[116:119], v38 offset:42624
	s_waitcnt lgkmcnt(3)
	v_mfma_f32_16x16x32_bf16 v[108:111], v[120:123], v[16:19], v[108:111]
	ds_read_b128 v[120:123], v38 offset:42688
	s_waitcnt lgkmcnt(3)
	v_mfma_f32_16x16x32_bf16 v[108:111], v[124:127], v[12:15], v[108:111]
	s_waitcnt lgkmcnt(2)
	v_mfma_f32_16x16x32_bf16 v[108:111], v[112:115], v[8:11], v[108:111]
	s_waitcnt lgkmcnt(1)
	v_mfma_f32_16x16x32_bf16 v[108:111], v[116:119], v[4:7], v[108:111]
	s_waitcnt lgkmcnt(0)
; #define GAS __attribute__((address_space(1)))
; #define LAS __attribute__((address_space(3)))
; __device__ __forceinline__ unsigned cvt_pk_bf16(float lo, float hi) { unsigned r; asm volatile("v_cvt_pk_bf16_f32 %0, %1, %2" : "=v"(r) : "v"(lo), "v"(hi)); return r; }
; __device__ __forceinline__ void pmat_phase(const Frame& F, const bf16_t* Q, const bf16_t* K, bf16_t* PB, int half) {
;     ...
;         for (int jt = 0; jt < 8; ++jt) { f32x4 st = {0.f, 0.f, 0.f, 0.f};
; #pragma unroll
;             for (int ks = 0; ks < 8; ++ks) { const bf16x8 Kf = *(const LAS bf16x8*)(bK + 16 * jt * PS + 64 * ks); st = __builtin_amdgcn_mfma_f32_16x16x32_bf16(Kf, Qf[ks], st, 0, 0, 0); }
; #pragma unroll
;             for (int r = 0; r < 4; ++r) { const int jj = 16 * jt + 4 * quad + r;
;                 st[r] *= __builtin_amdgcn_exp2f(jj <= i_abs ? lgf * (float)(-jj - 1) : lgb * (float)(jj - 128)); }
;             *(GAS u32x2*)(pout + 16 * jt + lpo) = (u32x2){cvt_pk_bf16(st[0], st[1]), cvt_pk_bf16(st[2], st[3])}; }
	v_mfma_f32_16x16x32_bf16 v[108:111], v[120:123], v[0:3], v[108:111]
	v_mul_f32_e32 v112, s12, v80
	v_cndmask_b32_e64 v107, v107, v112, s[72:73]
	v_exp_f32_e32 v107, v107
	v_mul_f32_e32 v112, s12, v82
	s_nop 3
	v_mul_f32_e32 v107, v107, v108
	v_mul_f32_e32 v108, s23, v81
	v_cndmask_b32_e64 v108, v108, v112, s[74:75]
	v_exp_f32_e32 v108, v108
	v_mul_f32_e32 v112, s12, v84
	v_mul_f32_e32 v108, v108, v109
	v_mul_f32_e32 v109, s23, v83
	v_cndmask_b32_e64 v109, v109, v112, s[76:77]
	v_exp_f32_e32 v109, v109
	v_mul_f32_e32 v112, s12, v86
	v_cvt_pk_bf16_f32 v108, v107, v108
	v_mul_f32_e32 v107, s23, v87
	v_mul_f32_e32 v109, v109, v110
	v_mul_f32_e32 v110, s23, v85
	v_cndmask_b32_e64 v110, v110, v112, s[78:79]
	v_exp_f32_e32 v110, v110
	s_nop 0
	v_mul_f32_e32 v110, v110, v111
	v_cvt_pk_bf16_f32 v109, v109, v110
	global_store_dwordx2 v[36:37], v[108:109], off offset:160
	ds_read_b128 v[108:111], v38 offset:50688
	ds_read_b128 v[112:115], v38 offset:50752
	ds_read_b128 v[116:119], v38 offset:50816
	ds_read_b128 v[120:123], v38 offset:50880
	ds_read_b128 v[124:127], v38 offset:50944
	s_waitcnt lgkmcnt(4)
	v_mfma_f32_16x16x32_bf16 v[108:111], v[108:111], v[28:31], 0
	s_waitcnt lgkmcnt(3)
	v_mfma_f32_16x16x32_bf16 v[108:111], v[112:115], v[24:27], v[108:111]
	ds_read_b128 v[112:115], v38 offset:51008
	s_waitcnt lgkmcnt(3)
	v_mfma_f32_16x16x32_bf16 v[108:111], v[116:119], v[20:23], v[108:111]
	ds_read_b128 v[116:119], v38 offset:51072
	s_waitcnt lgkmcnt(3)
	v_mfma_f32_16x16x32_bf16 v[108:111], v[120:123], v[16:19], v[108:111]
	ds_read_b128 v[120:123], v38 offset:51136
	s_waitcnt lgkmcnt(3)
	v_mfma_f32_16x16x32_bf16 v[108:111], v[124:127], v[12:15], v[108:111]
	s_waitcnt lgkmcnt(2)
	v_mfma_f32_16x16x32_bf16 v[108:111], v[112:115], v[8:11], v[108:111]
	s_waitcnt lgkmcnt(1)
	v_mfma_f32_16x16x32_bf16 v[108:111], v[116:119], v[4:7], v[108:111]
	s_waitcnt lgkmcnt(0)
	v_mfma_f32_16x16x32_bf16 v[108:111], v[120:123], v[0:3], v[108:111]
	v_mul_f32_e32 v112, s12, v88
	v_cndmask_b32_e64 v107, v107, v112, s[80:81]
	v_exp_f32_e32 v107, v107
	v_mul_f32_e32 v112, s12, v90
	s_nop 3
	v_mul_f32_e32 v107, v107, v108
	v_mul_f32_e32 v108, s23, v89
	v_cndmask_b32_e64 v108, v108, v112, s[82:83]
	v_exp_f32_e32 v108, v108
	v_mul_f32_e32 v112, s12, v92
	v_mul_f32_e32 v108, v108, v109
	v_mul_f32_e32 v109, s23, v91
	v_cndmask_b32_e64 v109, v109, v112, s[84:85]
	v_exp_f32_e32 v109, v109
	v_mul_f32_e32 v112, s12, v94
	v_cvt_pk_bf16_f32 v108, v107, v108
	v_mul_f32_e32 v109, v109, v110
	v_mul_f32_e32 v110, s23, v93
	v_cndmask_b32_e64 v110, v110, v112, s[86:87]
	v_exp_f32_e32 v110, v110
	s_nop 0
	v_mul_f32_e32 v110, v110, v111
	v_cvt_pk_bf16_f32 v109, v109, v110
	global_store_dwordx2 v[36:37], v[108:109], off offset:192
	ds_read_b128 v[108:111], v38 offset:59136
	ds_read_b128 v[112:115], v38 offset:59200
	ds_read_b128 v[116:119], v38 offset:59264
	ds_read_b128 v[120:123], v38 offset:59328
	ds_read_b128 v[124:127], v38 offset:59392
	s_waitcnt lgkmcnt(4)
	v_mfma_f32_16x16x32_bf16 v[28:31], v[108:111], v[28:31], 0
	ds_read_b128 v[108:111], v38 offset:59456
	s_waitcnt lgkmcnt(4)
	v_mfma_f32_16x16x32_bf16 v[24:27], v[112:115], v[24:27], v[28:31]
	ds_read_b128 v[112:115], v38 offset:59520
	s_waitcnt lgkmcnt(4)
	v_mfma_f32_16x16x32_bf16 v[20:23], v[116:119], v[20:23], v[24:27]
	ds_read_b128 v[116:119], v38 offset:59584
	s_waitcnt lgkmcnt(4)
	v_mfma_f32_16x16x32_bf16 v[16:19], v[120:123], v[16:19], v[20:23]
	s_waitcnt lgkmcnt(3)
	v_mfma_f32_16x16x32_bf16 v[12:15], v[124:127], v[12:15], v[16:19]
	s_waitcnt lgkmcnt(2)
	v_mfma_f32_16x16x32_bf16 v[8:11], v[108:111], v[8:11], v[12:15]
	s_waitcnt lgkmcnt(1)
	v_mfma_f32_16x16x32_bf16 v[4:7], v[112:115], v[4:7], v[8:11]
	s_waitcnt lgkmcnt(0)
	v_mfma_f32_16x16x32_bf16 v[0:3], v[116:119], v[0:3], v[4:7]
	s_nop 2
	v_mul_f32_e32 v4, s23, v95
	v_mul_f32_e32 v5, s12, v96
	v_cndmask_b32_e64 v4, v4, v5, s[88:89]
	v_exp_f32_e32 v4, v4
	v_mul_f32_e32 v5, s12, v98
	v_mul_f32_e32 v0, v4, v0
	v_mul_f32_e32 v4, s23, v97
	v_cndmask_b32_e64 v4, v4, v5, s[90:91]
	v_exp_f32_e32 v4, v4
	v_mul_f32_e32 v5, s12, v100
	v_mul_f32_e32 v1, v4, v1
	v_mul_f32_e32 v4, s23, v99
	v_cndmask_b32_e64 v4, v4, v5, s[92:93]
	v_exp_f32_e32 v4, v4
	v_mul_f32_e32 v5, s12, v102
	v_cvt_pk_bf16_f32 v0, v0, v1
	v_mul_f32_e32 v2, v4, v2
	v_mul_f32_e32 v4, s23, v101
	v_cndmask_b32_e64 v4, v4, v5, s[94:95]
	v_exp_f32_e32 v4, v4
	s_nop 0
	v_mul_f32_e32 v3, v4, v3
	v_cvt_pk_bf16_f32 v1, v2, v3
	global_store_dwordx2 v[36:37], v[0:1], off offset:224
	v_lshl_add_u64 v[36:37], v[36:37], 0, s[30:31]
	s_barrier
	s_cmp_lg_u32 s100, 0
	s_cbranch_scc1 .LBB0_915
	v_readlane_b32 s94, v255, 49
	s_mov_b32 s93, 0x10000
	v_readlane_b32 s95, v255, 50
